# split group barrier: prompt counter arrives after the 256x256 units, per-seam sample counters polled by sample-row consumers; small tiles overlap the barrier wait
# speedup vs baseline: 1.0301x; 1.0061x over previous
; #define LAS __attribute__((address_space(3)))
; __device__ __forceinline__ unsigned xb_xcc_id() { return (unsigned)__builtin_amdgcn_s_getreg((3 << 11) | 20) & 0xFu; }
; __global__ void __launch_bounds__(NWAVES * 64, 2) hybrid_fwd(Args args) {
;     extern __shared__ __attribute__((aligned(16))) unsigned char lds_raw[];
;     LAS unsigned char* lds = (LAS unsigned char*)lds_raw;
;     volatile LAS unsigned* MISC = (volatile LAS unsigned*)(lds + MISC_OFF);
;     if (threadIdx.x < 64) MISC[threadIdx.x] = 0u;
;     __syncthreads();
;     (void)xcd_barrier_post((unsigned*)(args.ws + WS_CTL), MISC + 8);
;     if (threadIdx.x == 0) atomicOr((unsigned*)(args.ws + WS_CTL) + GB_MASK(blockIdx.x & 7), 1u << xb_xcc_id());
;     unsigned gbn = 0;
;     for (int ph = args.ph_lo; ph < args.ph_hi;) {
;         int tid = threadIdx.x; asm volatile("" : "+v"(tid));
;         const int lane = tid & 63, wave = __builtin_amdgcn_readfirstlane(tid >> 6);
;         const int G = gridDim.x; const int bx = blockIdx.x;
;         unsigned char* ws = args.ws;
.LBB0_7:
	s_or_b64 exec, exec, s[0:1]
	s_load_dwordx2 s[38:39], s[80:81], 0xd0
	s_waitcnt lgkmcnt(0)
	s_cmp_ge_i32 s38, s39
	s_cbranch_scc1 .LBB0_733
	s_add_u32 s0, s80, 0xd8
	s_addc_u32 s1, s81, 0
	v_writelane_b32 v253, s0, 2
	s_add_u32 s56, s34, 0x200000
	s_load_dwordx16 s[8:23], s[80:81], 0x88
	v_writelane_b32 v253, s1, 3
	s_addc_u32 s0, s35, 0
	v_writelane_b32 v253, s0, 4
	s_ashr_i32 s0, s60, 31
	v_writelane_b32 v253, s0, 5
	s_lshr_b32 s0, s0, 29
	s_add_i32 s0, s60, s0
	s_ashr_i32 s3, s0, 3
	s_and_b32 s0, s0, -8
	s_sub_i32 s4, s60, s0
	s_add_u32 s0, s34, 0x100000
	s_addc_u32 s1, s35, 0
	s_add_u32 s62, s34, 0xf700000
	v_writelane_b32 v253, s0, 6
	s_addc_u32 s63, s35, 0
	v_lshrrev_b32_e32 v1, 20, v0
	v_writelane_b32 v253, s1, 7
	s_waitcnt lgkmcnt(0)
	s_add_u32 s0, s22, 0x4dfc000
	v_writelane_b32 v253, s0, 8
	s_addc_u32 s0, s23, 0
	v_writelane_b32 v253, s0, 9
	s_add_u32 s0, s22, 0x423c000
	v_writelane_b32 v253, s0, 10
	s_addc_u32 s0, s23, 0
	v_writelane_b32 v253, s0, 11
	s_add_u32 s0, s22, 0x4e7c000
	v_writelane_b32 v253, s0, 12
	s_addc_u32 s0, s23, 0
	v_writelane_b32 v253, s0, 13
	s_add_u32 s0, s22, 0x4674000
	v_writelane_b32 v253, s0, 14
	s_addc_u32 s0, s23, 0
	s_add_u32 s64, s34, 0x7500000
	s_addc_u32 s65, s35, 0
	v_writelane_b32 v253, s0, 15
	s_add_u32 s0, s22, 0x4df4000
	v_writelane_b32 v253, s0, 16
	s_addc_u32 s0, s23, 0
	v_writelane_b32 v253, s0, 17
	s_add_u32 s0, s22, 0x4200000
	v_writelane_b32 v253, s0, 18
	s_addc_u32 s0, s23, 0
	v_writelane_b32 v253, s0, 19
	s_add_u32 s0, s22, 0x45fc000
	v_writelane_b32 v253, s0, 20
	s_addc_u32 s0, s23, 0
	s_add_u32 s82, s34, 0xfe00000
	s_addc_u32 s83, s35, 0
	s_cmpk_lt_i32 s60, 0x400
	v_writelane_b32 v253, s0, 21
	s_cselect_b64 s[0:1], -1, 0
	v_writelane_b32 v253, s0, 22
	s_cmp_gt_i32 s4, -1
	v_lshrrev_b32_e32 v0, 10, v0
	v_writelane_b32 v253, s1, 23
	s_cselect_b64 s[0:1], -1, 0
	v_writelane_b32 v253, s0, 24
	v_or_b32_e32 v0, v0, v1
	v_mov_b32_e32 v129, 0
	v_writelane_b32 v253, s1, 25
	s_lshl_b32 s0, s4, 7
	s_cmp_eq_u64 s[34:35], 0
	s_cselect_b64 s[6:7], -1, 0
	s_cmp_lg_u64 s[34:35], 0
	v_writelane_b32 v253, s6, 26
	s_cselect_b64 s[66:67], -1, 0
	s_cmpk_lt_i32 s60, 0x200
	v_writelane_b32 v253, s7, 27
	s_cselect_b64 s[6:7], -1, 0
	v_writelane_b32 v253, s6, 28
	s_cmpk_lt_i32 s60, 0x100
	v_mov_b64_e32 v[130:131], 0x400
	v_writelane_b32 v253, s7, 29
	s_cselect_b64 s[6:7], -1, 0
	v_writelane_b32 v253, s6, 30
	v_mov_b64_e32 v[132:133], 0x3ff
	v_mov_b32_e32 v168, 0x358637bd
	v_writelane_b32 v253, s7, 31
	s_add_u32 s6, s34, 0x5400000
	s_addc_u32 s7, s35, 0
	v_writelane_b32 v253, s6, 32
	s_lshl_b32 s1, s60, 9
	s_cmp_gt_i32 s38, -1
	v_writelane_b32 v253, s7, 33
	v_writelane_b32 v253, s1, 34
	s_cselect_b64 s[6:7], -1, 0
	v_writelane_b32 v253, s6, 35
	v_mov_b32_e32 v169, 0x1000
	v_mov_b32_e32 v170, 0x2000
	v_writelane_b32 v253, s7, 36
	s_add_u32 s6, s34, 0x200
	s_addc_u32 s7, s35, 0
	v_writelane_b32 v253, s6, 37
	v_mov_b32_e32 v171, 1
	v_mov_b32_e32 v172, 0x82000
	v_writelane_b32 v253, s7, 38
	s_add_u32 s6, s34, 0x1000
	s_addc_u32 s7, s35, 0
	v_writelane_b32 v253, s6, 39
	v_mov_b32_e32 v173, 0xffffef80
	v_mov_b32_e32 v174, 0xfffff800
	v_writelane_b32 v253, s7, 40
	s_add_u32 s6, s34, 0x1100
	s_addc_u32 s7, s35, 0
	v_writelane_b32 v253, s6, 41
	v_mov_b32_e32 v175, 0x1080
	v_mov_b32_e32 v176, 0xbc800000
	v_writelane_b32 v253, s7, 42
	s_add_u32 s6, s34, 0x1200
	s_addc_u32 s7, s35, 0
	v_writelane_b32 v253, s6, 43
	v_mov_b32_e32 v177, 0x3c800000
	v_mov_b32_e32 v178, 0x3c00
	v_writelane_b32 v253, s7, 44
	s_add_u32 s6, s34, 0x1300
	s_addc_u32 s7, s35, 0
	v_writelane_b32 v253, s6, 45
	v_mov_b32_e32 v179, 0x880
	v_mov_b32_e32 v180, 0x7800
	v_writelane_b32 v253, s7, 46
	s_add_u32 s6, s34, 0x3400
	s_addc_u32 s7, s35, 0
	v_writelane_b32 v253, s6, 47
	v_mov_b32_e32 v181, 0x440000
	v_mov_b32_e32 v182, 0xffc00000
	v_writelane_b32 v253, s7, 48
	s_add_u32 s6, s34, 0x3500
	s_addc_u32 s7, s35, 0
	s_lshl_b32 s1, s60, 8
	v_writelane_b32 v253, s6, 49
	s_and_b32 s1, s1, 0x700
	s_lshl_b32 s2, s60, 6
	v_writelane_b32 v253, s7, 50
	s_add_u32 s1, s34, s1
	v_writelane_b32 v253, s2, 51
	s_addc_u32 s2, s35, 0
	s_add_u32 s6, s1, 0x9000
	s_addc_u32 s7, s2, 0
	v_writelane_b32 v253, s6, 52
	v_mov_b32_e32 v183, 0x3a800000
	v_mov_b32_e32 v184, 0x7cf
	v_writelane_b32 v253, s7, 53
	s_add_u32 s6, s1, 0x8000
	s_addc_u32 s7, s2, 0
	v_writelane_b32 v253, s6, 54
	s_movk_i32 s1, 0x3ff
	v_and_or_b32 v0, v0, s1, v135
	v_writelane_b32 v253, s7, 55
	v_writelane_b32 v253, s4, 56
	v_writelane_b32 v253, s8, 57
	s_cmp_lt_i32 s4, 0
	s_mul_i32 s1, s4, 0x81
	v_writelane_b32 v254, s15, 0
	v_writelane_b32 v254, s16, 1
	v_writelane_b32 v254, s17, 2
	v_writelane_b32 v254, s18, 3
	s_cselect_b32 s0, s1, s0
	v_writelane_b32 v254, s19, 4
	s_add_i32 s0, s0, s3
	v_writelane_b32 v254, s20, 5
	s_ashr_i32 s1, s0, 31
	v_writelane_b32 v254, s21, 6
	s_lshr_b32 s1, s1, 28
	v_writelane_b32 v254, s22, 7
	s_add_i32 s1, s0, s1
	v_writelane_b32 v254, s23, 8
	s_and_b32 s2, s1, -16
	v_writelane_b32 v254, s3, 9
	s_sub_i32 s6, s0, s2
	s_ashr_i32 s2, s1, 4
	s_ashr_i32 s0, s1, 7
	v_writelane_b32 v254, s2, 10
	s_mov_b32 s4, s6
	s_ashr_i32 s1, s0, 31
	s_lshl_b32 s2, s2, 20
	s_ashr_i32 s7, s6, 31
	v_writelane_b32 v254, s4, 11
	s_lshl_b64 s[0:1], s[0:1], 23
	s_and_b32 s2, s2, 0x700000
	v_writelane_b32 v254, s5, 12
	s_lshl_b64 s[4:5], s[6:7], 19
	s_add_u32 s0, s22, s0
	s_addc_u32 s1, s23, s1
	v_writelane_b32 v254, s4, 13
	s_add_u32 s0, s0, s2
	s_addc_u32 s1, s1, 0
	v_writelane_b32 v254, s5, 14
	s_add_u32 s2, s0, 0x80000
	v_writelane_b32 v254, s0, 15
	s_addc_u32 s3, s1, 0
	v_writelane_b32 v253, s9, 58
	v_writelane_b32 v254, s1, 16
	v_writelane_b32 v254, s2, 17
	s_add_i32 s0, 0, 0x2940
	v_writelane_b32 v253, s10, 59
	v_writelane_b32 v254, s3, 18
	v_writelane_b32 v254, s0, 19
	s_add_i32 s0, 0, 0x2b40
	v_writelane_b32 v254, s0, 20
	s_add_i32 s0, 0, 0x23f20
	v_writelane_b32 v254, s0, 21
	s_add_i32 s0, 0, 0x23f24
	v_writelane_b32 v254, s0, 22
	v_cmp_eq_u32_e64 s[0:1], 0, v0
	v_writelane_b32 v253, s11, 60
	v_writelane_b32 v253, s12, 61
	v_writelane_b32 v254, s0, 23
	v_writelane_b32 v253, s13, 62
	v_writelane_b32 v253, s14, 63
	v_writelane_b32 v254, s1, 24
	s_load_dwordx2 s[0:1], s[80:81], 0x38
	v_mov_b32_e32 v185, 0x1580
	s_mov_b32 s61, 0x10000
	s_mov_b32 s37, 0x18000
	s_mov_b32 s57, 0x8000
	s_waitcnt lgkmcnt(0)
; #define LAS __attribute__((address_space(3)))
; __device__ __forceinline__ unsigned xb_xcc_id() { return (unsigned)__builtin_amdgcn_s_getreg((3 << 11) | 20) & 0xFu; }
; __global__ void __launch_bounds__(NWAVES * 64, 2) hybrid_fwd(Args args) {
;     extern __shared__ __attribute__((aligned(16))) unsigned char lds_raw[];
;     LAS unsigned char* lds = (LAS unsigned char*)lds_raw;
;     volatile LAS unsigned* MISC = (volatile LAS unsigned*)(lds + MISC_OFF);
;     if (threadIdx.x < 64) MISC[threadIdx.x] = 0u;
;     __syncthreads();
;     (void)xcd_barrier_post((unsigned*)(args.ws + WS_CTL), MISC + 8);
;     if (threadIdx.x == 0) atomicOr((unsigned*)(args.ws + WS_CTL) + GB_MASK(blockIdx.x & 7), 1u << xb_xcc_id());
;     unsigned gbn = 0;
;     for (int ph = args.ph_lo; ph < args.ph_hi;) {
;         int tid = threadIdx.x; asm volatile("" : "+v"(tid));
;         const int lane = tid & 63, wave = __builtin_amdgcn_readfirstlane(tid >> 6);
;         const int G = gridDim.x; const int bx = blockIdx.x;
;         unsigned char* ws = args.ws;
	v_writelane_b32 v254, s0, 25
	s_mov_b32 s91, 0xffff0000
	s_mov_b32 s58, 0x20000
	v_writelane_b32 v254, s1, 26
	s_load_dwordx4 s[0:3], s[80:81], 0x20
	s_mov_b32 s59, 0x30000
	s_movk_i32 s90, 0x7fff
	s_movk_i32 s78, 0x1080
	s_mov_b32 s79, 0x800000
	s_waitcnt lgkmcnt(0)
	v_writelane_b32 v254, s0, 27
	s_movk_i32 s33, 0x84
	s_mov_b32 s69, 0
	v_writelane_b32 v254, s1, 28
	v_writelane_b32 v254, s2, 29
	v_writelane_b32 v254, s3, 30
	s_load_dwordx8 s[0:7], s[80:81], 0x0
	s_mov_b32 s85, 0
	s_mov_b64 s[76:77], 0x80
	s_mov_b32 s20, 0x3c800000
	s_waitcnt lgkmcnt(0)
	v_writelane_b32 v254, s0, 31
	s_nop 1
	v_writelane_b32 v254, s1, 32
	v_writelane_b32 v254, s2, 33
	v_writelane_b32 v254, s3, 34
	v_writelane_b32 v254, s4, 35
	v_writelane_b32 v254, s5, 36
	v_writelane_b32 v254, s6, 37
	v_writelane_b32 v254, s7, 38
	s_load_dwordx16 s[0:15], s[80:81], 0x48
	s_waitcnt lgkmcnt(0)
	v_writelane_b32 v254, s0, 39
	s_nop 1
	v_writelane_b32 v254, s1, 40
	v_writelane_b32 v254, s2, 41
	v_writelane_b32 v254, s3, 42
	v_writelane_b32 v254, s4, 43
	v_writelane_b32 v254, s5, 44
	v_writelane_b32 v254, s6, 45
	v_writelane_b32 v254, s7, 46
	v_writelane_b32 v254, s8, 47
	v_writelane_b32 v254, s9, 48
	v_writelane_b32 v254, s10, 49
	v_writelane_b32 v254, s11, 50
	v_writelane_b32 v254, s12, 51
	v_writelane_b32 v254, s13, 52
	v_writelane_b32 v254, s14, 53
	v_writelane_b32 v254, s15, 54
	v_writelane_b32 v254, s56, 55
	v_writelane_b32 v254, s80, 56
	s_nop 1
	v_writelane_b32 v254, s81, 57
	s_mov_b32 s99, 0
	s_mov_b32 s101, 0
	s_branch .LBB0_13

; #define LAS __attribute__((address_space(3)))
; __device__ __forceinline__ unsigned xb_ld(unsigned* p)              { return __hip_atomic_load(p, __ATOMIC_RELAXED, __HIP_MEMORY_SCOPE_AGENT); }
; __device__ __forceinline__ unsigned xb_xcc_id() { return (unsigned)__builtin_amdgcn_s_getreg((3 << 11) | 20) & 0xFu; }
; __global__ void __launch_bounds__(NWAVES * 64, 2) hybrid_fwd(Args args) {
;     ...
;         if (ph < args.ph_hi) {
;             const int kd = (ph - 2) % 7;
;             const bool local = (gridDim.x == 256) && ph >= 2; (void)kd;
;             if (args.ph_lo < 0) cg::this_grid().sync();
;             else if (local) { unsigned* ctl = (unsigned*)(args.ws + WS_CTL); const int x = blockIdx.x & 7; ++gbn;
;                 const unsigned mk = xb_ld(&ctl[GB_MASK(x)]); group_barrier(ctl, x, 32u * gbn, (mk & (mk - 1u)) == 0u && mk != 0u); }
;             else { XcdBarrier b; b.bar = (unsigned*)(args.ws + WS_CTL); b.x = xb_xcc_id(); b.st = (volatile LAS unsigned*)(lds + MISC_OFF) + 8; xcd_barrier(b); }
.LBB0_11:
	s_mov_b32 s99, 0
	s_mov_b32 s101, 0
	s_mov_b64 s[0:1], 0
	s_waitcnt lgkmcnt(0)

; #define PG8_STAGE(bufoff, gbase, voff) do { _Pragma("unroll") for (int _i = 0; _i < 2; ++_i) \
;         __builtin_amdgcn_global_load_lds((const unsigned*)((const char*)(gbase) + (voff)[_i]), (PG8_LAS unsigned*)(lds + (bufoff) + ldsw + _i * 8192), 16, 0, 0); } while (0)
; #define PG8_WAIT_V(n) asm volatile("s_waitcnt vmcnt(" #n ")" ::: "memory")
; #define PG8_BAR __builtin_amdgcn_s_barrier()
; template <class Epi, class Sched, bool ALIGN_EPI = false, bool SP2 = false>
; __device__ __forceinline__ void gemm_phase(PG8_LAS unsigned char* lds, const Gemm g, const Sched& S, const Epi& E, const int tid) {
;     const int wid = __builtin_amdgcn_readfirstlane(tid >> 6), lane = tid & 63, wr = wid >> 2, wc = wid & 3, fr = lane & 15, fq = lane >> 4;
;     const int K = g.K, nt = K / BK;
;     unsigned voffA[2], voffB[2];
; #pragma unroll
;     for (int i = 0; i < 2; ++i) { int R, C; stage_rc(tid * 16 + i * 8192, R, C); const int Rb = Epi::PERM ? ((R & ~31) + perm32(R & 31)) : R;
;         voffA[i] = (unsigned)(R * g.lda + C) * 2u; voffB[i] = (unsigned)(Rb * g.ldb + C) * 2u; }
;     const size_t kstep = (size_t)(BK * 2);
;     const size_t hstepA = (size_t)HALF * g.lda * 2, hstepB = (size_t)HALF * g.ldb * 2;
;     const size_t tstepA = 2 * hstepA, tstepB = 2 * hstepB;
;     const unsigned ldsw = (unsigned)wid * 1024u;
;     const int aoff = lds_byte(wr * 64 + fr, fq * 8), boff = lds_byte(wc * 32 + fr, fq * 8);
;     ...
;     const char* cA = (const char*)g.A + (size_t)(cur.pm >> 3) * g.gsa + (size_t)(cur.pm & 7) * tstepA; const char* cB = (const char*)g.Bt + (size_t)cur.pn * tstepB;
;     S.a_ready(cur);
;     if constexpr (SP2) {
;         PG8_STAGE(PG8_SB(0, 0), cB, voffB); PG8_STAGE(PG8_SB(0, 1), cB + hstepB, voffB); PG8_STAGE(PG8_SA(0, 0), cA, voffA); PG8_STAGE(PG8_SA(0, 1), cA + hstepA, voffA);
;         if (wr == 1) PG8_BAR;
;         PG8_WAIT_V(2); PG8_BAR;
;         PG8_STAGE(PG8_SB(1, 0), cB + kstep, voffB); PG8_STAGE(PG8_SA(1, 0), cA + kstep, voffA); PG8_STAGE(PG8_SB(1, 1), cB + hstepB + kstep, voffB);
;         PG8_WAIT_V(6); PG8_BAR;
.LBB0_22:
	v_readlane_b32 s4, v253, 22
	s_add_u32 s0, s92, 0x700000
	v_readlane_b32 s5, v253, 23
	s_addc_u32 s1, s93, 0
	v_readfirstlane_b32 s2, v186
	s_andn2_b64 vcc, exec, s[4:5]
	v_and_b32_e32 v153, 15, v186
	s_cbranch_vccnz .LBB0_58
	v_readlane_b32 s100, v253, 54
	v_readlane_b32 s101, v253, 55
	s_lshl_b32 vcc_lo, s69, 2
	s_add_u32 vcc_lo, vcc_lo, 0x2000
	s_add_u32 s100, s100, vcc_lo
	s_addc_u32 s101, s101, 0
	s_waitcnt vmcnt(0)
	v_lshlrev_b32_e32 v0, 4, v186
	v_add_u32_e32 v1, 0x2000, v0
	v_ashrrev_i32_e32 v2, 31, v1
	v_lshrrev_b32_e32 v2, 22, v2
	v_add_u32_e32 v2, v1, v2
	v_ashrrev_i32_e32 v4, 10, v2
	v_mul_i32_i24_e32 v2, 0x400, v4
	v_sub_u32_e32 v1, v1, v2
	v_lshrrev_b32_e32 v2, 4, v1
	v_bitop3_b32 v1, v2, v1, 32 bitop3:0x6c
	v_ashrrev_i32_e32 v2, 31, v1
	v_lshrrev_b32_e32 v2, 26, v2
	v_add_u32_e32 v2, v1, v2
	v_lshlrev_b32_e32 v3, 3, v4
	v_ashrrev_i32_e32 v5, 6, v2
	v_and_b32_e32 v3, -16, v3
	v_add_u32_e32 v3, v5, v3
	v_and_b32_e32 v6, 3, v5
	s_mov_b32 s4, 0x1fffe0
	v_lshrrev_b32_e32 v7, 2, v3
	v_lshlrev_b32_e32 v8, 1, v3
	v_and_b32_e32 v2, 0xc0, v2
	v_and_or_b32 v6, v3, s4, v6
	v_and_b32_e32 v7, 4, v7
	v_and_b32_e32 v8, 24, v8
	v_sub_u32_e32 v1, v1, v2
	v_or3_b32 v7, v6, v7, v8
	v_lshlrev_b32_e32 v6, 5, v4
	v_ashrrev_i16_sdwa v1, v171, sext(v1) dst_sel:DWORD dst_unused:UNUSED_PAD src0_sel:DWORD src1_sel:BYTE_0
	v_and_b32_e32 v8, 32, v6
	v_bfe_i32 v6, v1, 0, 16
	v_add_lshl_u32 v1, v8, v6, 1
	v_lshl_add_u32 v136, v7, 11, v1
	v_lshl_add_u32 v138, v3, 12, v1
	v_bfe_i32 v1, v186, 27, 1
	v_lshrrev_b32_e32 v1, 22, v1
	v_add_u32_e32 v1, v0, v1
	v_and_b32_e32 v1, 0xfffffc00, v1
	v_sub_u32_e32 v0, v0, v1
	v_lshrrev_b32_e32 v1, 4, v0
	v_ashrrev_i32_e32 v2, 31, v186
	v_bitop3_b32 v0, v1, v0, 32 bitop3:0x6c
	v_lshrrev_b32_e32 v2, 26, v2
	v_ashrrev_i32_e32 v1, 31, v0
	v_add_u32_e32 v2, v186, v2
	v_lshrrev_b32_e32 v1, 26, v1
	v_ashrrev_i32_e32 v8, 6, v2
	v_add_u32_e32 v1, v0, v1
	v_lshlrev_b32_e32 v2, 3, v8
	v_ashrrev_i32_e32 v7, 6, v1
	v_and_b32_e32 v2, -16, v2
	v_add_u32_e32 v2, v7, v2
	v_and_b32_e32 v3, 3, v7
	v_lshrrev_b32_e32 v9, 2, v2
	v_lshlrev_b32_e32 v10, 1, v2
	v_and_b32_e32 v1, 0xc0, v1
	s_ashr_i32 s6, s2, 6
	v_and_or_b32 v3, v2, s4, v3
	v_and_b32_e32 v9, 4, v9
	v_and_b32_e32 v10, 24, v10
	v_sub_u32_e32 v0, v0, v1
	s_mov_b32 s42, s68
	s_ashr_i32 s7, s2, 8
	s_lshl_b32 s68, s6, 10
	v_or3_b32 v3, v3, v9, v10
	v_lshlrev_b32_e32 v9, 5, v8
	v_ashrrev_i16_sdwa v0, v171, sext(v0) dst_sel:DWORD dst_unused:UNUSED_PAD src0_sel:DWORD src1_sel:BYTE_0
	v_readlane_b32 s4, v254, 13
	v_and_b32_e32 v10, 32, v9
	v_bfe_i32 v9, v0, 0, 16
	v_readlane_b32 s5, v254, 14
	s_add_u32 s18, s0, s4
	s_mov_b32 s43, s69
	v_add_lshl_u32 v0, v10, v9, 1
	s_addc_u32 s19, s1, s5
	s_add_i32 s69, s68, 0
	v_lshl_add_u32 v140, v3, 11, v0
	s_add_i32 m0, s69, 0x10000
	v_lshl_add_u32 v142, v2, 12, v0
	global_load_lds_dwordx4 v140, s[18:19]
	s_add_i32 m0, s69, 0x12000
	s_add_u32 s4, s18, 0x40000
	global_load_lds_dwordx4 v136, s[18:19]
	s_addc_u32 s5, s19, 0
	s_add_i32 m0, s69, 0x14000
	s_add_i32 s70, s69, 0x2000
	global_load_lds_dwordx4 v140, s[4:5]
	s_add_i32 m0, s69, 0x16000
	s_add_i32 s71, s69, 0x4000
	global_load_lds_dwordx4 v136, s[4:5]
	v_readlane_b32 s4, v254, 15
	s_mov_b32 m0, s69
	v_readlane_b32 s5, v254, 16
	s_add_i32 s74, s69, 0x6000
	v_mov_b32_e32 v141, v129
	v_mov_b32_e32 v137, v129
	s_cmp_eq_u32 s7, 1
	s_mov_b64 s[40:41], s[38:39]
	global_load_lds_dwordx4 v142, s[4:5]
	s_mov_b32 m0, s70
	v_lshl_add_u64 v[0:1], s[18:19], 0, v[140:141]
	global_load_lds_dwordx4 v138, s[4:5]
	v_readlane_b32 s4, v254, 17
	s_mov_b32 m0, s71
	v_readlane_b32 s5, v254, 18
	v_lshl_add_u64 v[2:3], s[18:19], 0, v[136:137]
	s_nop 3
	global_load_lds_dwordx4 v142, s[4:5]
	s_mov_b32 m0, s74
	s_nop 0
	global_load_lds_dwordx4 v138, s[4:5]
	s_cselect_b64 s[4:5], -1, 0
	s_cmp_lg_u32 s7, 1
	s_cbranch_scc1 .LBB0_25
	s_barrier

;     __device__ __forceinline__ void operator()(const f32x4 (&acc)[2][2][4][2], const Unit& u, int wr, int wc, int fr, int fq) const {
;         const int row0 = u.pm * BM + wr * 64 + fr; const int col0 = u.pn * BM + wc * 32 + 8 * fq;
; #pragma unroll
;         for (int ai = 0; ai < 2; ++ai)
; #pragma unroll
;             for (int m = 0; m < 4; ++m) { const int row_ = row0 + ai * HALF + m * 16; bf16_t* rowp = O + (size_t)(row_ >> 11) * gs + (size_t)(row_ & 2047) * ldc + col0; const float sc = rs ? rs[row0 + ai * HALF + m * 16] : 1.f;
.Lupepi_go:
	global_load_dword v255, v129, s[100:101] sc1

; #define PG8_WAIT_V(n) asm volatile("s_waitcnt vmcnt(" #n ")" ::: "memory")
; #define PG8_BAR __builtin_amdgcn_s_barrier()
; __device__ __forceinline__ unsigned xb_ld(unsigned* p)              { return __hip_atomic_load(p, __ATOMIC_RELAXED, __HIP_MEMORY_SCOPE_AGENT); }
; __device__ __forceinline__ unsigned xb_add(unsigned* p, unsigned v) { return __hip_atomic_fetch_add(p, v, __ATOMIC_RELAXED, __HIP_MEMORY_SCOPE_AGENT); }
; #define XB_SPIN(cond, bar) do { unsigned _sp = 0; while (cond) { __builtin_amdgcn_s_sleep(1); \
;     if ((++_sp & 255u) == 0u) { if (xb_ld(&(bar)[XB_TMO])) break; if (_sp > XB_SPIN_CAP) { atomicAdd(&(bar)[XB_TMO], 1u); break; } } } } while (0)
; template <class Epi, class Sched, bool ALIGN_EPI = false, bool SP2 = false>
; __device__ __forceinline__ void gemm_phase(PG8_LAS unsigned char* lds, const Gemm g, const Sched& S, const Epi& E, const int tid) {
;     ...
;     PG8_WAIT_V(0);
;     if constexpr (!ALIGN_EPI) { if (wr == 0) PG8_BAR; }
;     PG8_BAR;
; __device__ __forceinline__ void group_barrier(unsigned* ctl, int x, unsigned target, bool coloc) {
;     asm volatile("s_waitcnt vmcnt(0)" ::: "memory");
;     __syncthreads();
;     if (threadIdx.x == 0) {
;         if (!coloc) { __builtin_amdgcn_fence(__ATOMIC_RELEASE, "agent"); asm volatile("s_waitcnt vmcnt(0)" ::: "memory"); }
;         (void)xb_add(&ctl[GB_CNT(x)], 1u);
;         XB_SPIN(xb_ld(&ctl[GB_CNT(x)]) < target, ctl);
.LBB0_57:
	s_waitcnt vmcnt(0)
	s_mov_b64 s[38:39], s[40:41]
	v_readlane_b32 s56, v254, 55
	s_mov_b32 s37, 0x18000
	s_mov_b32 s57, 0x8000
	s_mov_b32 s58, 0x20000
	s_mov_b32 s59, 0x30000
	s_mov_b32 s68, s42
	s_mov_b32 s69, s43
	v_readlane_b32 s70, v254, 58
	s_barrier
	s_cmp_lt_u32 s38, 2
	s_cbranch_scc1 .Lap_skip_up
	s_mov_b32 s99, 1
	v_cmp_eq_u32_e32 vcc, 0, v135
	s_and_saveexec_b64 s[100:101], vcc
	s_cbranch_execz .Lap_done_up
	s_cmp_eq_u32 s98, 1
	s_cbranch_scc1 .Lap_nowb_up
	buffer_wbl2 sc1
	s_waitcnt vmcnt(0)
.Lap_nowb_up:
	v_readlane_b32 vcc_lo, v253, 54
	v_readlane_b32 vcc_hi, v253, 55
	s_nop 4
	global_atomic_add v129, v171, vcc
.Lap_done_up:
	s_mov_b64 exec, s[100:101]
.Lap_skip_up:
.LBB0_58:
	v_readlane_b32 s4, v253, 28
	v_readlane_b32 s5, v253, 29
	s_andn2_b64 vcc, exec, s[4:5]
	v_readlane_b32 s4, v253, 57
	v_readlane_b32 s18, v254, 7
	v_readlane_b32 s19, v254, 8
	v_readlane_b32 s5, v253, 58
	v_readlane_b32 s6, v253, 59
	v_readlane_b32 s7, v253, 60
	v_readlane_b32 s8, v253, 61
	v_readlane_b32 s9, v253, 62
	v_readlane_b32 s10, v253, 63
	v_readlane_b32 s11, v254, 0
	v_readlane_b32 s12, v254, 1
	v_readlane_b32 s13, v254, 2
	v_readlane_b32 s14, v254, 3
	v_readlane_b32 s15, v254, 4
	v_readlane_b32 s16, v254, 5
	v_readlane_b32 s17, v254, 6
	s_cbranch_vccnz .LBB0_61
	v_readfirstlane_b32 vcc_hi, v255
	s_cmp_ge_u32 vcc_hi, 32
	s_cbranch_scc1 .Lws_done_up
	s_mov_b32 vcc_lo, s69
	s_cmp_eq_u32 vcc_lo, 0
	s_cbranch_scc1 .Lws_done_up
	v_readlane_b32 s100, v253, 54
	v_readlane_b32 s101, v253, 55
	s_lshl_b32 vcc_lo, vcc_lo, 2
	s_add_u32 vcc_lo, vcc_lo, 0x2000
	s_add_u32 s100, s100, vcc_lo
	s_addc_u32 s101, s101, 0
	s_mov_b32 m0, 0
.Lws_up:
	global_load_dword v255, v129, s[100:101] sc1
	s_waitcnt vmcnt(0)
	v_readfirstlane_b32 vcc_hi, v255
	s_cmp_ge_u32 vcc_hi, 32
	s_cbranch_scc1 .Lws_done_up
	s_sleep 1
	s_add_u32 m0, m0, 1
	s_cmp_lt_u32 m0, 0x40000
	s_cbranch_scc1 .Lws_up
.Lws_done_up:
	s_waitcnt vmcnt(3)
	v_ashrrev_i32_e32 v1, 31, v186
	v_lshrrev_b32_e32 v1, 29, v1
	v_add_u32_e32 v1, v186, v1
	s_waitcnt vmcnt(0)
	v_bfe_u32 v0, v186, 4, 2
	v_ashrrev_i32_e32 v13, 3, v1
	v_bfe_i32 v1, v186, 28, 1
	v_lshlrev_b32_e32 v2, 3, v0
	v_lshlrev_b32_e32 v14, 10, v0
	v_lshlrev_b32_e32 v0, 3, v186
	v_lshrrev_b32_e32 v1, 26, v1
	v_add_u32_e32 v1, v0, v1
	v_and_b32_e32 v1, 0xffffffc0, v1
	v_lshlrev_b32_e32 v3, 2, v153
	v_lshl_add_u32 v4, v186, 5, 0
	v_sub_u32_e32 v0, v0, v1
	v_add_u32_e32 v5, 0x10000, v4
	v_add_u32_e32 v6, 0x10010, v4
	v_add_u32_e32 v7, 0x14000, v4
	v_add_u32_e32 v8, 0x14010, v4
	v_add_u32_e32 v9, 0x18000, v4
	v_add_u32_e32 v10, 0x18010, v4
	v_add_u32_e32 v11, 0x1c000, v4
	v_add_u32_e32 v12, 0x1c010, v4
	v_ashrrev_i32_e32 v1, 31, v0
	v_add3_u32 v14, 0, v3, v14
	s_waitcnt lgkmcnt(0)
	s_lshl_b32 s2, s3, 6
	v_lshlrev_b32_e32 v2, 1, v2
	v_readlane_b32 s6, v253, 51
	s_mov_b32 s7, s60

; #define LAS __attribute__((address_space(3)))
; __global__ void __launch_bounds__(NWAVES * 64, 2) hybrid_fwd(Args args) {
;     ...
;                     int lane = tid & 63; asm volatile("" : "+v"(lane));
;                     if (u < NU_SGU) { sgu_unit(ZP_PROMPT(u >> 6), CP_PROMPT(u >> 6), SGW, args.in[17] + (size_t)l * GW, args.in[18] + (size_t)l * GW, args.in[20] + (size_t)l * 4 * 128, u >> 2, u & 3, (LAS bf16*)scr, lane); continue; }
;                     int r = u - NU_SGU;
;                     if (r < NU_CONV) { const int seg = r >> 2, h = r & 3, seq = seg >> 6, t0 = (seg & 63) * 32;
;                         conv_unit_p(ZP_PROMPT(seq), CP_PROMPT(seq), out + OUT_CONV_P + (size_t)l * NBP * 30 * GW, args.in[13] + (size_t)l * 31 * GW, args.in[14] + (size_t)l * GW, args.in[15] + (size_t)l * GW, args.in[16] + (size_t)l * GW, seq, t0, h, scr, lane);
;                         continue; }
;                     r -= NU_CONV;
;                     if (r < 2 * NU_SEG) { const int ty = r / NU_SEG, q = r % NU_SEG, seg = q >> 2, h = q & 3, seq = seg >> 5, t0 = (seg & 31) * 64;
;                         if (ty == 0) { float* np = out + OUT_POOL_P + (size_t)l * NBP * 15 * GW;
;                             if (h == 0) pool_unit_p<2>(ZP_PROMPT(seq), CP_PROMPT(seq), np, seq, t0, h, lane); else if (h == 1) pool_unit_p<4>(ZP_PROMPT(seq), CP_PROMPT(seq), np, seq, t0, h, lane);
;                             else if (h == 2) pool_unit_p<8>(ZP_PROMPT(seq), CP_PROMPT(seq), np, seq, t0, h, lane); else pool_unit_p<16>(ZP_PROMPT(seq), CP_PROMPT(seq), np, seq, t0, h, lane); }
;                         else short_unit_p(ZP_PROMPT(seq), CP_PROMPT(seq), out + OUT_SHORT_P + (size_t)l * NBP * 2 * GW, args.in[21] + (size_t)l * 3 * GW, seq, t0, h, lane);
;                         continue; }
;                     r -= 2 * NU_SEG;
;                     { const int ty = r >> 9, q = r & 511, seq = q >> 2, h = q & 3;
.LBB0_114:
	s_and_b64 vcc, exec, s[4:5]
	s_cbranch_vccz .LBB0_417
	v_mov_b32_e32 v124, v134
	s_cmpk_gt_i32 s87, 0x1ff
	s_mov_b64 s[4:5], -1
	s_cbranch_scc0 .LBB0_413
	s_cmpk_gt_u32 s87, 0x9ff
	s_cbranch_scc0 .LBB0_360
	s_cmpk_gt_u32 s87, 0x11ff
	s_cbranch_scc0 .LBB0_141
	s_cmp_eq_u32 s101, -1
	s_cbranch_scc1 .Lws_skip_mx
	v_readlane_b32 vcc_lo, v252, 2
	s_cmp_eq_u32 vcc_lo, 0
	s_cbranch_scc1 .Lws_done_mx
	v_readlane_b32 s100, v253, 54
	v_readlane_b32 s101, v253, 55
	s_lshl_b32 vcc_lo, vcc_lo, 2
	s_add_u32 vcc_lo, vcc_lo, 0x2000
	s_add_u32 s100, s100, vcc_lo
	s_addc_u32 s101, s101, 0
	s_mov_b32 m0, 0

; __device__ __forceinline__ float bf2f(bf16 b) { return __uint_as_float(((unsigned)b) << 16); }
; __device__ __forceinline__ unsigned f2bf(float f) { unsigned u = __float_as_uint(f); return (u + 0x7fffu + ((u >> 16) & 1u)) >> 16; }
; __device__ __forceinline__ void sgu_sample_unit(const bf16* __restrict__ Z, bf16* __restrict__ CAT, const float* __restrict__ Wf, const float* __restrict__ lg, const float* __restrict__ lb, ...
;     const int c = h * 64 + lane; const size_t rowbase = (size_t)MP + (size_t)seq * ST;
;     const float gg = lg[c], bb = lb[c];
;     float vn[ST];
; #pragma unroll
;     for (int t = 0; t < ST; ++t) { const float v = bf2f(Z[(rowbase + t) * ZP + 1024 + c]); const float mean = wave_sum(v) * (1.f / 64.f); const float d = v - mean; const float var = wave_sum(d * d) * (1.f / 64.f);
;         vn[t] = d * rsqrtf(var + EPS) * gg + bb; vout[((size_t)seq * ST + t) * GW + c] = vn[t]; }
; #pragma unroll
;     for (int t = 0; t < ST; ++t) { float sv = sb[h * 128 + t];
; #pragma unroll
;         for (int s = 0; s <= t; ++s) sv += Wf[((size_t)h * 128 + t) * 128 + s] * vn[s];
;         const float u = bf2f(Z[(rowbase + t) * ZP + 768 + c]);
;         CAT[(rowbase + t) * DP + 512 + c] = (bf16)f2bf(u * sv); }
.Lws_done_mx:
	s_mov_b32 s101, -1
.Lws_skip_mx:
	s_add_i32 s2, s87, 0xffffee00
	s_bfe_u32 s6, s87, 0x70002
	s_and_b32 s7, s87, 3
	s_cmpk_gt_u32 s2, 0x1ff
	s_cbranch_scc0 .LBB0_138
	s_lshr_b32 s2, s2, 9
	s_cmp_lt_i32 s2, 2
	s_cbranch_scc1 .LBB0_125
	s_cmp_lg_u32 s2, 2
	s_cbranch_scc0 .LBB0_122
	s_lshr_b32 s2, s6, 4
	s_waitcnt vmcnt(0)
	v_mul_u32_u24_e32 v0, s2, v172
	v_readlane_b32 s10, v252, 18
	v_readfirstlane_b32 s4, v0
	s_add_u32 s4, s62, s4
	s_addc_u32 s5, s63, 0
	s_lshl_b32 s2, s2, 6
	s_bitset1_b32 s2, 14
	v_mul_hi_i32_i24_e32 v1, s2, v173
	v_mul_i32_i24_e32 v0, s2, v173
	v_lshl_add_u64 v[2:3], s[4:5], 0, v[0:1]
	v_mul_i32_i24_e32 v1, s2, v174
	v_mul_hi_i32_i24_e32 v0, s2, v174
	v_readfirstlane_b32 s2, v1
	v_readfirstlane_b32 s8, v0
	s_add_u32 s2, s4, s2
	v_lshl_add_u32 v0, s7, 6, v124
	s_addc_u32 s4, s5, s8
	v_ashrrev_i32_e32 v1, 31, v0
	s_add_u32 s2, s2, 0x48000
	v_lshlrev_b64 v[4:5], 2, v[0:1]
	s_addc_u32 s4, s4, 0
	s_lshl_b32 s8, s6, 2
	v_lshl_add_u64 v[6:7], s[50:51], 0, v[4:5]
	s_or_b32 s5, s8, 0x4000
	global_load_dword v15, v[6:7], off
	v_lshl_add_u64 v[6:7], s[0:1], 0, v[4:5]
	v_readlane_b32 s11, v252, 19
	global_load_dword v14, v[6:7], off
	v_mov_b32_e32 v10, v129
	v_lshl_add_u64 v[8:9], s[10:11], 0, v[4:5]
	v_mad_u64_u32 v[6:7], s[10:11], s5, v175, v[2:3]
	v_lshlrev_b64 v[4:5], 1, v[0:1]
	v_lshl_add_u64 v[6:7], v[6:7], 0, v[4:5]
	global_load_ushort v0, v[6:7], off offset:2048
	s_lshl_b32 s84, s6, 12
	v_mov_b32_e32 v12, v129
	v_mov_b32_e32 v18, v129
	v_readlane_b32 s10, v252, 16
	v_readlane_b32 s11, v252, 17
	s_lshl_b32 s5, s5, 11
	global_load_ushort v6, v[6:7], off offset:1536
	s_waitcnt vmcnt(1)
	v_lshlrev_b32_e32 v0, 16, v0
	s_nop 1
	v_add_f32_dpp v1, v0, v0 quad_perm:[1,0,3,2] row_mask:0xf bank_mask:0xf bound_ctrl:1
	s_waitcnt vmcnt(0)
	v_lshlrev_b32_e32 v6, 16, v6
	v_add_f32_dpp v1, v1, v1 quad_perm:[2,3,0,1] row_mask:0xf bank_mask:0xf bound_ctrl:1
	s_nop 1
	v_add_f32_dpp v1, v1, v1 row_half_mirror row_mask:0xf bank_mask:0xf bound_ctrl:1
	s_nop 1
	v_add_f32_dpp v1, v1, v1 row_mirror row_mask:0xf bank_mask:0xf bound_ctrl:1
	s_nop 1
	v_mov_b32_dpp v10, v1 row_bcast:15 row_mask:0xa bank_mask:0xf
	v_add_f32_e32 v1, v1, v10
	v_mov_b32_e32 v10, v129
	s_nop 1
	v_mov_b32_dpp v10, v1 row_bcast:31 row_mask:0xc bank_mask:0xf
	v_add_f32_e32 v1, v1, v10
	v_mov_b32_e32 v10, v129
	v_readlane_b32 s9, v1, 63
	s_nop 1
	v_fmac_f32_e32 v0, s9, v176
	v_mul_f32_e32 v1, v0, v0
	s_nop 1
	v_mov_b32_dpp v10, v1 quad_perm:[1,0,3,2] row_mask:0xf bank_mask:0xf
	v_fmac_f32_e32 v10, v0, v0
	s_nop 1
	v_add_f32_dpp v1, v10, v10 quad_perm:[2,3,0,1] row_mask:0xf bank_mask:0xf bound_ctrl:1
	v_mov_b32_e32 v10, v129
	s_nop 0
	v_add_f32_dpp v1, v1, v1 row_half_mirror row_mask:0xf bank_mask:0xf bound_ctrl:1
	s_nop 1
	v_add_f32_dpp v1, v1, v1 row_mirror row_mask:0xf bank_mask:0xf bound_ctrl:1
	s_nop 1
	v_mov_b32_dpp v10, v1 row_bcast:15 row_mask:0xa bank_mask:0xf
	v_add_f32_e32 v1, v1, v10
	v_mov_b32_e32 v10, v129
	s_nop 1
	v_mov_b32_dpp v10, v1 row_bcast:31 row_mask:0xc bank_mask:0xf
	v_add_f32_e32 v1, v1, v10
	s_nop 0
	v_readlane_b32 s9, v1, 63
	s_nop 1
	v_fma_f32 v1, s9, v177, v168
	v_cmp_gt_f32_e32 vcc, s79, v1
	v_mul_f32_e32 v10, 0x4b800000, v1
	v_mad_u64_u32 v[2:3], s[8:9], s8, v175, v[2:3]
	v_cndmask_b32_e32 v1, v1, v10, vcc
	v_rsq_f32_e32 v1, v1
	v_lshl_add_u64 v[2:3], v[2:3], 0, v[4:5]
	s_mov_b32 s8, 0x4201000
	v_mul_f32_e32 v10, 0x45800000, v1
	v_cndmask_b32_e32 v1, v1, v10, vcc
	v_add_co_u32_e32 v10, vcc, s8, v2
	v_mul_f32_e32 v0, v0, v1
	s_nop 0
	v_addc_co_u32_e32 v11, vcc, 0, v3, vcc
	v_fma_f32 v16, v15, v0, v14
	v_lshl_add_u64 v[0:1], v[8:9], 0, s[84:85]
	global_load_ushort v8, v[10:11], off offset:2176
	s_waitcnt vmcnt(0)
	v_lshlrev_b32_e32 v8, 16, v8
	s_nop 1
	v_add_f32_dpp v9, v8, v8 quad_perm:[1,0,3,2] row_mask:0xf bank_mask:0xf bound_ctrl:1
	global_store_dword v[0:1], v16, off
	s_nop 0
	v_add_f32_dpp v9, v9, v9 quad_perm:[2,3,0,1] row_mask:0xf bank_mask:0xf bound_ctrl:1
	s_nop 1
	v_add_f32_dpp v9, v9, v9 row_half_mirror row_mask:0xf bank_mask:0xf bound_ctrl:1
	s_nop 1
	v_add_f32_dpp v9, v9, v9 row_mirror row_mask:0xf bank_mask:0xf bound_ctrl:1
	s_nop 1
	v_mov_b32_dpp v12, v9 row_bcast:15 row_mask:0xa bank_mask:0xf
	v_add_f32_e32 v9, v9, v12
	v_mov_b32_e32 v12, v129
	s_nop 1
	v_mov_b32_dpp v12, v9 row_bcast:31 row_mask:0xc bank_mask:0xf
	v_add_f32_e32 v9, v9, v12
	v_mov_b32_e32 v12, v129
	v_readlane_b32 s8, v9, 63
	s_nop 1
	v_fmac_f32_e32 v8, s8, v176
	v_mul_f32_e32 v9, v8, v8
	s_nop 1
	v_mov_b32_dpp v12, v9 quad_perm:[1,0,3,2] row_mask:0xf bank_mask:0xf
	v_fmac_f32_e32 v12, v8, v8
	s_nop 1
	v_add_f32_dpp v9, v12, v12 quad_perm:[2,3,0,1] row_mask:0xf bank_mask:0xf bound_ctrl:1
	v_mov_b32_e32 v12, v129
	s_nop 0
	v_add_f32_dpp v9, v9, v9 row_half_mirror row_mask:0xf bank_mask:0xf bound_ctrl:1
	s_nop 1
	v_add_f32_dpp v9, v9, v9 row_mirror row_mask:0xf bank_mask:0xf bound_ctrl:1
	s_nop 1
	v_mov_b32_dpp v12, v9 row_bcast:15 row_mask:0xa bank_mask:0xf
	v_add_f32_e32 v9, v9, v12
	v_mov_b32_e32 v12, v129
	s_nop 1
	v_mov_b32_dpp v12, v9 row_bcast:31 row_mask:0xc bank_mask:0xf
	v_add_f32_e32 v9, v9, v12
	s_nop 0
	v_readlane_b32 s8, v9, 63
	s_nop 1
	v_fma_f32 v9, s8, v177, v168
	v_cmp_gt_f32_e32 vcc, s79, v9
	v_mul_f32_e32 v12, 0x4b800000, v9
	s_mov_b32 s8, 0x4202000
	v_cndmask_b32_e32 v9, v9, v12, vcc
	v_rsq_f32_e32 v9, v9
	s_nop 0
	v_mul_f32_e32 v12, 0x45800000, v9
	v_cndmask_b32_e32 v9, v9, v12, vcc
	v_add_co_u32_e32 v12, vcc, s8, v2
	v_mul_f32_e32 v8, v8, v9
	s_nop 0
	v_addc_co_u32_e32 v13, vcc, 0, v3, vcc
	v_fma_f32 v17, v15, v8, v14
	global_load_ushort v8, v[12:13], off offset:2304
	s_waitcnt vmcnt(0)
; __device__ __forceinline__ float bf2f(bf16 b) { return __uint_as_float(((unsigned)b) << 16); }
; __device__ __forceinline__ unsigned f2bf(float f) { unsigned u = __float_as_uint(f); return (u + 0x7fffu + ((u >> 16) & 1u)) >> 16; }
; __device__ __forceinline__ void sgu_sample_unit(const bf16* __restrict__ Z, bf16* __restrict__ CAT, const float* __restrict__ Wf, const float* __restrict__ lg, const float* __restrict__ lb, ...
;     ...
; #pragma unroll
;     for (int t = 0; t < ST; ++t) { const float v = bf2f(Z[(rowbase + t) * ZP + 1024 + c]); const float mean = wave_sum(v) * (1.f / 64.f); const float d = v - mean; const float var = wave_sum(d * d) * (1.f / 64.f);
;         vn[t] = d * rsqrtf(var + EPS) * gg + bb; vout[((size_t)seq * ST + t) * GW + c] = vn[t]; }
; #pragma unroll
;     for (int t = 0; t < ST; ++t) { float sv = sb[h * 128 + t];
; #pragma unroll
;         for (int s = 0; s <= t; ++s) sv += Wf[((size_t)h * 128 + t) * 128 + s] * vn[s];
;         const float u = bf2f(Z[(rowbase + t) * ZP + 768 + c]);
;         CAT[(rowbase + t) * DP + 512 + c] = (bf16)f2bf(u * sv); }
	v_lshlrev_b32_e32 v8, 16, v8
	s_nop 1
	v_add_f32_dpp v9, v8, v8 quad_perm:[1,0,3,2] row_mask:0xf bank_mask:0xf bound_ctrl:1
	global_store_dword v[0:1], v17, off offset:1024
	s_nop 0
	v_add_f32_dpp v9, v9, v9 quad_perm:[2,3,0,1] row_mask:0xf bank_mask:0xf bound_ctrl:1
	s_nop 1
	v_add_f32_dpp v9, v9, v9 row_half_mirror row_mask:0xf bank_mask:0xf bound_ctrl:1
	s_nop 1
	v_add_f32_dpp v9, v9, v9 row_mirror row_mask:0xf bank_mask:0xf bound_ctrl:1
	s_nop 1
	v_mov_b32_dpp v18, v9 row_bcast:15 row_mask:0xa bank_mask:0xf
	v_add_f32_e32 v9, v9, v18
	v_mov_b32_e32 v18, v129
	s_nop 1
	v_mov_b32_dpp v18, v9 row_bcast:31 row_mask:0xc bank_mask:0xf
	v_add_f32_e32 v9, v9, v18
	v_mov_b32_e32 v18, v129
	v_readlane_b32 s8, v9, 63
	s_nop 1
	v_fmac_f32_e32 v8, s8, v176
	v_mul_f32_e32 v9, v8, v8
	s_nop 1
	v_mov_b32_dpp v18, v9 quad_perm:[1,0,3,2] row_mask:0xf bank_mask:0xf
	v_fmac_f32_e32 v18, v8, v8
	s_nop 1
	v_add_f32_dpp v9, v18, v18 quad_perm:[2,3,0,1] row_mask:0xf bank_mask:0xf bound_ctrl:1
	v_mov_b32_e32 v18, v129
	s_nop 0
	v_add_f32_dpp v9, v9, v9 row_half_mirror row_mask:0xf bank_mask:0xf bound_ctrl:1
	s_nop 1
	v_add_f32_dpp v9, v9, v9 row_mirror row_mask:0xf bank_mask:0xf bound_ctrl:1
	s_nop 1
	v_mov_b32_dpp v18, v9 row_bcast:15 row_mask:0xa bank_mask:0xf
	v_add_f32_e32 v9, v9, v18
	v_mov_b32_e32 v18, v129
	s_nop 1
	v_mov_b32_dpp v18, v9 row_bcast:31 row_mask:0xc bank_mask:0xf
	v_add_f32_e32 v9, v9, v18
	s_nop 0
	v_readlane_b32 s8, v9, 63
	s_nop 1
	v_fma_f32 v9, s8, v177, v168
	v_cmp_gt_f32_e32 vcc, s79, v9
	v_mul_f32_e32 v18, 0x4b800000, v9
	s_mov_b32 s8, 0x4203000
	v_cndmask_b32_e32 v9, v9, v18, vcc
	v_rsq_f32_e32 v9, v9
	s_nop 0
	v_mul_f32_e32 v18, 0x45800000, v9
	v_cndmask_b32_e32 v9, v9, v18, vcc
	v_mul_f32_e32 v8, v8, v9
	v_fma_f32 v21, v15, v8, v14
	v_add_co_u32_e32 v8, vcc, s8, v2
	v_mov_b32_e32 v18, v129
	s_nop 0
	v_addc_co_u32_e32 v9, vcc, 0, v3, vcc
	global_load_ushort v2, v[8:9], off offset:2432
	s_waitcnt vmcnt(0)
	v_lshlrev_b32_e32 v2, 16, v2
	s_nop 1
	v_add_f32_dpp v3, v2, v2 quad_perm:[1,0,3,2] row_mask:0xf bank_mask:0xf bound_ctrl:1
	global_store_dword v[0:1], v21, off offset:2048
	s_nop 0
	v_add_f32_dpp v3, v3, v3 quad_perm:[2,3,0,1] row_mask:0xf bank_mask:0xf bound_ctrl:1
	s_nop 1
	v_add_f32_dpp v3, v3, v3 row_half_mirror row_mask:0xf bank_mask:0xf bound_ctrl:1
	s_nop 1
	v_add_f32_dpp v3, v3, v3 row_mirror row_mask:0xf bank_mask:0xf bound_ctrl:1
	s_nop 1
	v_mov_b32_dpp v18, v3 row_bcast:15 row_mask:0xa bank_mask:0xf
	v_add_f32_e32 v3, v3, v18
	v_mov_b32_e32 v18, v129
	s_nop 1
	v_mov_b32_dpp v18, v3 row_bcast:31 row_mask:0xc bank_mask:0xf
	v_add_f32_e32 v3, v3, v18
	v_mov_b32_e32 v18, v129
	v_readlane_b32 s8, v3, 63
	s_nop 1
	v_fmac_f32_e32 v2, s8, v176
	v_mul_f32_e32 v3, v2, v2
	s_nop 1
	v_mov_b32_dpp v18, v3 quad_perm:[1,0,3,2] row_mask:0xf bank_mask:0xf
	v_fmac_f32_e32 v18, v2, v2
	s_nop 1
	v_add_f32_dpp v3, v18, v18 quad_perm:[2,3,0,1] row_mask:0xf bank_mask:0xf bound_ctrl:1
	v_mov_b32_e32 v18, v129
	s_nop 0
	v_add_f32_dpp v3, v3, v3 row_half_mirror row_mask:0xf bank_mask:0xf bound_ctrl:1
	s_nop 1
	v_add_f32_dpp v3, v3, v3 row_mirror row_mask:0xf bank_mask:0xf bound_ctrl:1
	s_nop 1
	v_mov_b32_dpp v18, v3 row_bcast:15 row_mask:0xa bank_mask:0xf
	v_add_f32_e32 v3, v3, v18
	v_mov_b32_e32 v18, v129
	s_nop 1
	v_mov_b32_dpp v18, v3 row_bcast:31 row_mask:0xc bank_mask:0xf
	v_add_f32_e32 v3, v3, v18
	s_nop 0
	v_readlane_b32 s8, v3, 63
	s_nop 1
	v_fma_f32 v3, s8, v177, v168
	v_cmp_gt_f32_e32 vcc, s79, v3
	v_mul_f32_e32 v18, 0x4b800000, v3
	s_lshl_b32 s8, s7, 9
	v_cndmask_b32_e32 v3, v3, v18, vcc
	v_rsq_f32_e32 v3, v3
	s_nop 0
	v_mul_f32_e32 v18, 0x45800000, v3
	v_cndmask_b32_e32 v3, v3, v18, vcc
	v_mul_f32_e32 v2, v2, v3
	v_fmac_f32_e32 v14, v15, v2
	global_store_dword v[0:1], v14, off offset:3072
	v_mov_b32_e32 v0, s8
	s_lshl_b32 s8, s7, 16
	v_mov_b32_e32 v15, s8
	global_load_dwordx4 v[0:3], v0, s[94:95]
	s_add_u32 s8, s2, s5
	global_load_dword v18, v15, s[10:11]
	s_addc_u32 s9, s4, 0
	s_lshl_b32 s5, s6, 13
	s_waitcnt vmcnt(0)
	v_fma_f32 v0, v16, v18, v0
	v_mul_f32_e32 v0, v0, v6
	v_bfe_u32 v6, v0, 16, 1
	v_add3_u32 v0, v0, v6, s90
	v_lshl_add_u64 v[6:7], s[8:9], 0, v[4:5]
	global_store_short_d16_hi v[6:7], v0, off offset:1024
	global_load_dwordx2 v[6:7], v15, s[10:11] offset:512
	s_or_b32 s8, s5, 0x2000800
	global_load_dwordx3 v[18:20], v15, s[10:11] offset:1024
	s_add_u32 s8, s2, s8
	s_addc_u32 s9, s4, 0
	s_waitcnt vmcnt(1)
	v_fma_f32 v0, v16, v6, v1
	global_load_ushort v1, v[10:11], off offset:1664
	v_fmac_f32_e32 v0, v17, v7
	s_waitcnt vmcnt(0)
	v_lshlrev_b32_e32 v1, 16, v1
	v_mul_f32_e32 v0, v0, v1
	v_bfe_u32 v1, v0, 16, 1
	v_add3_u32 v6, v0, v1, s90
	v_lshl_add_u64 v[0:1], s[8:9], 0, v[4:5]
	global_store_short_d16_hi v[0:1], v6, off offset:1024
	global_load_ushort v1, v[12:13], off offset:1792
	v_fma_f32 v0, v16, v18, v2
	v_fmac_f32_e32 v0, v17, v19
	v_fmac_f32_e32 v0, v21, v20
	s_or_b32 s8, s5, 0x2001000
	s_add_u32 s8, s2, s8
	global_load_dwordx4 v[10:13], v15, s[10:11] offset:1536
	s_addc_u32 s9, s4, 0
	s_or_b32 s5, s5, 0x2001800
	s_waitcnt vmcnt(1)
	v_lshlrev_b32_e32 v1, 16, v1
	v_mul_f32_e32 v0, v0, v1
	v_bfe_u32 v1, v0, 16, 1
	v_add3_u32 v2, v0, v1, s90
	v_lshl_add_u64 v[0:1], s[8:9], 0, v[4:5]
	global_store_short_d16_hi v[0:1], v2, off offset:1024
	global_load_ushort v0, v[8:9], off offset:1920
	s_waitcnt vmcnt(2)
	v_fmac_f32_e32 v3, v16, v10
	v_fmac_f32_e32 v3, v17, v11
	v_fmac_f32_e32 v3, v21, v12
	v_fmac_f32_e32 v3, v14, v13
	s_add_u32 s8, s2, s5
	s_addc_u32 s9, s4, 0
	s_mov_b64 s[4:5], 0
	s_waitcnt vmcnt(0)
	v_lshlrev_b32_e32 v0, 16, v0
	v_mul_f32_e32 v0, v3, v0
	v_bfe_u32 v1, v0, 16, 1
	v_add3_u32 v2, v0, v1, s90
	v_lshl_add_u64 v[0:1], s[8:9], 0, v[4:5]
	global_store_short_d16_hi v[0:1], v2, off offset:1024

; __global__ void __launch_bounds__(NWAVES * 64, 2) hybrid_fwd(Args args) {
;     ...
;                   if (nk > 0) { EwRow r0, r1, r2;
;                     { const int ma = EW_ROW(0); ew_load(r0, X16 + (size_t)ma * 2 * DM, OB + (size_t)ma * OP, lane); }
;                     { const int kb = 1 < nk ? 1 : 0; const int mb = EW_ROW(kb); ew_load(r1, X16 + (size_t)mb * 2 * DM, OB + (size_t)mb * OP, lane); }
; #pragma unroll 1
;                     for (int k = 0; k < nk; ++k) {
;                         { const int kc = k + 2 < nk ? k + 2 : k; const int mc = EW_ROW(kc); ew_load(r2, X16 + (size_t)mc * 2 * DM, OB + (size_t)mc * OP, lane); }
;                         const int m = EW_ROW(k);
;                         ew_finish(r0, gg, X + (size_t)m * DM, X16 + (size_t)m * 2 * DM, dst16, RS + m, write_xn, lane);
.Lres_ws:
	s_cmp_eq_u32 s101, -1
	s_cbranch_scc1 .Lws_skip_rs
	s_mov_b32 vcc_lo, s69
	s_cmp_eq_u32 vcc_lo, 0
	s_cbranch_scc1 .Lws_done_rs
	v_readlane_b32 s100, v253, 54
	v_readlane_b32 s101, v253, 55
	s_lshl_b32 vcc_lo, vcc_lo, 2
	s_add_u32 vcc_lo, vcc_lo, 0x2000
	s_add_u32 s100, s100, vcc_lo
	s_addc_u32 s101, s101, 0
	s_mov_b32 m0, 0

; __global__ void __launch_bounds__(NWAVES * 64, 2) hybrid_fwd(Args args) {
;     ...
; #pragma unroll 1
;                 for (int ui = 0; ; ++ui) {
;                     int u;
;                     if (NGW != 2048) { u = ui * NGW + gw; if (u >= NU) break; }
.Lws_skip_rs:
	s_branch .LBB0_433
.LBB0_445:
	s_mov_b64 s[72:73], 0
	s_mov_b32 s87, s68

; #define PG8_STAGE(bufoff, gbase, voff) do { _Pragma("unroll") for (int _i = 0; _i < 2; ++_i) \
;         __builtin_amdgcn_global_load_lds((const unsigned*)((const char*)(gbase) + (voff)[_i]), (PG8_LAS unsigned*)(lds + (bufoff) + ldsw + _i * 8192), 16, 0, 0); } while (0)
; #define PG8_WAIT_V(n) asm volatile("s_waitcnt vmcnt(" #n ")" ::: "memory")
; #define PG8_BAR __builtin_amdgcn_s_barrier()
; template <class Epi, class Sched, bool ALIGN_EPI = false, bool SP2 = false>
; __device__ __forceinline__ void gemm_phase(PG8_LAS unsigned char* lds, const Gemm g, const Sched& S, const Epi& E, const int tid) {
;     ...
;     const char* cA = (const char*)g.A + (size_t)(cur.pm >> 3) * g.gsa + (size_t)(cur.pm & 7) * tstepA; const char* cB = (const char*)g.Bt + (size_t)cur.pn * tstepB;
;     S.a_ready(cur);
;     if constexpr (SP2) {
;         PG8_STAGE(PG8_SB(0, 0), cB, voffB); PG8_STAGE(PG8_SB(0, 1), cB + hstepB, voffB); PG8_STAGE(PG8_SA(0, 0), cA, voffA); PG8_STAGE(PG8_SA(0, 1), cA + hstepA, voffA);
;         if (wr == 1) PG8_BAR;
;         PG8_WAIT_V(2); PG8_BAR;
;         PG8_STAGE(PG8_SB(1, 0), cB + kstep, voffB); PG8_STAGE(PG8_SA(1, 0), cA + kstep, voffA); PG8_STAGE(PG8_SB(1, 1), cB + hstepB + kstep, voffB);
;         PG8_WAIT_V(6); PG8_BAR;
; __global__ void __launch_bounds__(NWAVES * 64, 2) hybrid_fwd(Args args) {
;     ...
;                 const bf16* A = k == 0 ? (const bf16*)args.out : (const bf16*)(ws + WS_H + (k == 2 ? GRP_CAT_OFF : 0));
;                 const bf16* Bt = (const bf16*)(wl + (k == 0 ? W_IN : k == 2 ? W_OUT : W_DN));
;                 bf16* O = (bf16*)(ws + (k == 0 ? WS_H : WS_O));
;                 const int N = k == 0 ? INW : DM, K = k == 5 ? FF : DM;
;                 const int lda_ = k == 5 ? FP : k == 0 ? 2 * DM : DP;
;                 pg8::Gemm g{A, Bt, MP, N, K, lda_, K + WPAD, k == 2 ? GRP_BYTES : (size_t)2048 * lda_ * 2}; pg8::StaticOrder S; S.init(MP, N, G, bx);
;                 pg8::EpiBf16<0> E{O, k == 0 ? ZP : OP, k == 0 ? GRP_BYTES / 2 : (size_t)2048 * OP, k == 0 ? (const float*)(ws + WS_RS) : nullptr};
;                 pg8::gemm_phase<pg8::EpiBf16<0>, pg8::StaticOrder, true, true>(lds, g, S, E, tid);
.LBB0_453:
	s_cmp_lg_u32 s86, 2
	s_cselect_b64 s[0:1], -1, 0
	s_cmp_eq_u32 s86, 2
	s_cselect_b64 s[18:19], -1, 0
	s_and_b64 s[4:5], s[18:19], exec
	s_cselect_b32 s2, 0x900000, 0
	s_mov_b32 s4, 0x480000
	s_cselect_b32 s10, s4, 0xf80000
	s_add_u32 s2, s64, s2
	s_mov_b32 s55, s69
	s_mov_b32 s54, s68
	s_mov_b64 s[24:25], s[66:67]
	s_mov_b64 s[22:23], s[62:63]
	s_mov_b32 s14, s60
	s_mov_b64 s[52:53], s[64:65]
	s_addc_u32 s11, s65, 0
	v_readlane_b32 s60, v253, 57
	s_and_b64 s[4:5], s[6:7], exec
	v_readlane_b32 s74, v254, 7
	v_readlane_b32 s75, v254, 8
	s_cselect_b32 s4, s2, s74
	s_mov_b32 s2, 0x5400000
	s_cselect_b32 s10, s10, 0
	s_cselect_b32 s5, s11, s75
	s_cselect_b32 s2, s2, 0x7500000
	s_add_u32 s10, s92, s10
	s_addc_u32 s11, s93, 0
	v_readlane_b32 s61, v253, 58
	v_readlane_b32 s62, v253, 59
	v_readlane_b32 s63, v253, 60
	v_readlane_b32 s66, v253, 63
	v_readlane_b32 s67, v254, 0
	s_add_u32 s12, s34, s2
	s_addc_u32 s13, s35, 0
	s_andn2_b64 vcc, exec, s[8:9]
	v_and_b32_e32 v153, 15, v186
	s_mov_b32 s60, s14
	s_mov_b64 s[62:63], s[22:23]
	s_mov_b64 s[66:67], s[24:25]
	s_mov_b32 s61, 0x10000
	v_readlane_b32 s64, v253, 61
	v_readlane_b32 s65, v253, 62
	v_readlane_b32 s68, v254, 1
	v_readlane_b32 s69, v254, 2
	v_readlane_b32 s70, v254, 3
	v_readlane_b32 s71, v254, 4
	v_readlane_b32 s72, v254, 5
	v_readlane_b32 s73, v254, 6
	s_cbranch_vccnz .LBB0_493
	v_readlane_b32 s100, v253, 54
	v_readlane_b32 s101, v253, 55
	s_lshl_b32 vcc_lo, s55, 2
	s_add_u32 vcc_lo, vcc_lo, 0x2000
	s_add_u32 s100, s100, vcc_lo
	s_addc_u32 s101, s101, 0
	s_waitcnt vmcnt(3)
	v_bfe_i32 v2, v186, 27, 1
	s_waitcnt vmcnt(0)
	v_lshlrev_b32_e32 v0, 4, v186
	v_lshrrev_b32_e32 v2, 22, v2
	v_add_u32_e32 v2, v0, v2
	v_and_b32_e32 v2, 0xfffffc00, v2
	v_sub_u32_e32 v2, v0, v2
	v_ashrrev_i32_e32 v1, 31, v186
	v_lshrrev_b32_e32 v3, 4, v2
	v_lshrrev_b32_e32 v1, 26, v1
	v_bitop3_b32 v2, v3, v2, 32 bitop3:0x6c
	v_add_u32_e32 v1, v186, v1
	s_waitcnt vmcnt(2)
	v_ashrrev_i32_e32 v4, 31, v2
	s_cmp_eq_u32 s86, 5
	v_ashrrev_i32_e32 v1, 6, v1
	v_lshrrev_b32_e32 v4, 26, v4
	s_movk_i32 s2, 0x1000
	s_cselect_b32 s14, 0x1040, s37
	v_lshlrev_b32_e32 v3, 3, v1
	v_add_u32_e32 v4, v2, v4
	s_cselect_b32 s9, s2, 0x400
	s_cselect_b32 s17, 12, 10
	s_cselect_b32 s97, 21, 19
	s_lshl_b32 s2, s14, 12
	v_and_b32_e32 v3, -16, v3
	v_ashrrev_i32_e32 v5, 6, v4
	v_lshlrev_b32_e32 v1, 5, v1
	s_and_b64 s[18:19], s[18:19], exec
	v_add_u32_e32 v3, v5, v3
	s_waitcnt vmcnt(0)
	v_and_b32_e32 v12, 32, v1
	v_and_b32_e32 v1, 0xc0, v4
	v_sub_u32_e32 v1, v2, v1
	v_lshlrev_b32_e32 v2, 1, v3
	v_lshrrev_b32_e32 v4, 2, v3
	v_and_b32_e32 v5, 3, v5
	s_mov_b32 s18, 0x7fffffe0
	v_ashrrev_i16_sdwa v1, v171, sext(v1) dst_sel:DWORD dst_unused:UNUSED_PAD src0_sel:DWORD src1_sel:BYTE_0
	v_and_b32_e32 v2, 24, v2
	v_and_b32_e32 v4, 4, v4
	v_and_or_b32 v5, v3, s18, v5
	v_bfe_i32 v13, v1, 0, 16
	v_or3_b32 v2, v5, v4, v2
	v_add_u32_e32 v1, v12, v13
	v_mul_lo_u32 v14, v3, s14
	v_lshlrev_b32_e32 v2, s17, v2
	v_add_u32_e32 v0, 0x2000, v0
	v_add_lshl_u32 v136, v1, v14, 1
	v_add_lshl_u32 v138, v2, v1, 1
	v_ashrrev_i32_e32 v1, 31, v0
	v_lshrrev_b32_e32 v1, 22, v1
	v_add_u32_e32 v1, v0, v1
	v_ashrrev_i32_e32 v1, 10, v1
	v_mul_i32_i24_e32 v2, 0x400, v1
	v_sub_u32_e32 v0, v0, v2
	v_lshrrev_b32_e32 v2, 4, v0
	v_bitop3_b32 v0, v2, v0, 32 bitop3:0x6c
	v_ashrrev_i32_e32 v3, 31, v0
	v_lshrrev_b32_e32 v3, 26, v3
	v_lshlrev_b32_e32 v2, 3, v1
	v_add_u32_e32 v3, v0, v3
	v_and_b32_e32 v2, -16, v2
	v_ashrrev_i32_e32 v4, 6, v3
	v_lshlrev_b32_e32 v1, 5, v1
	v_add_u32_e32 v2, v4, v2
	v_and_b32_e32 v15, 32, v1
	v_and_b32_e32 v1, 0xc0, v3
	v_sub_u32_e32 v0, v0, v1
	v_lshlrev_b32_e32 v1, 1, v2
	v_lshrrev_b32_e32 v3, 2, v2
	v_and_b32_e32 v4, 3, v4
	v_and_b32_e32 v1, 24, v1
	v_and_b32_e32 v3, 4, v3
	v_and_or_b32 v4, v2, s18, v4
	s_cselect_b32 s2, 0x1040000, s2
	s_ashr_i32 s8, s15, 6
	v_or3_b32 v1, v4, v3, v1
	s_lshl_b32 s80, s14, 9
	s_and_b32 s18, s41, 7
	s_ashr_i32 s89, s88, 31
	v_mul_lo_u32 v17, v2, s14
	v_lshlrev_b32_e32 v1, s17, v1
	s_ashr_i32 s17, s15, 8
	s_lshl_b32 s84, s14, 8
	s_lshl_b32 s21, s9, 8
	s_lshl_b32 s81, s8, 10
	s_ashr_i32 s14, s41, 3
	s_mul_i32 s23, s80, s18
	s_lshl_b64 s[18:19], s[88:89], s97
	s_add_u32 s92, s10, s18
	s_addc_u32 s93, s11, s19
	s_add_i32 s72, s81, 0
	s_add_i32 m0, s72, 0x10000
	v_ashrrev_i16_sdwa v0, v171, sext(v0) dst_sel:DWORD dst_unused:UNUSED_PAD src0_sel:DWORD src1_sel:BYTE_0
	s_mul_hi_i32 s22, s14, s2
	s_mul_i32 s14, s14, s2
	global_load_lds_dwordx4 v138, s[92:93]
	s_add_i32 m0, s72, 0x12000
	v_bfe_i32 v16, v0, 0, 16
	s_add_u32 s14, s4, s14
	v_add_u32_e32 v0, v15, v16
	s_addc_u32 s22, s5, s22
	v_add_lshl_u32 v142, v1, v0, 1
	s_add_u32 s18, s92, s21
	global_load_lds_dwordx4 v142, s[92:93]
	s_addc_u32 s19, s93, 0
	s_add_i32 m0, s72, 0x14000
	v_add_lshl_u32 v140, v0, v17, 1
	global_load_lds_dwordx4 v138, s[18:19]
	s_add_i32 m0, s72, 0x16000
	s_add_u32 s94, s14, s23
	s_addc_u32 s95, s22, 0
	s_add_i32 s73, s72, 0x2000
	global_load_lds_dwordx4 v142, s[18:19]
	s_mov_b32 m0, s72
	s_add_u32 s22, s94, s84
	global_load_lds_dwordx4 v136, s[94:95]
	s_mov_b32 m0, s73
	s_addc_u32 s23, s95, 0
	s_add_i32 s24, s72, 0x4000
	global_load_lds_dwordx4 v140, s[94:95]
	s_mov_b32 m0, s24
	s_add_i32 s25, s72, 0x6000
	global_load_lds_dwordx4 v136, s[22:23]
	s_mov_b32 m0, s25
	v_writelane_b32 v254, s38, 59
	global_load_lds_dwordx4 v140, s[22:23]
	v_mov_b32_e32 v139, v129
	v_mov_b32_e32 v143, v129
	v_mov_b32_e32 v137, v129
	v_mov_b32_e32 v141, v129
	s_cmp_eq_u32 s17, 1
	v_writelane_b32 v254, s39, 60
	v_lshl_add_u64 v[8:9], s[92:93], 0, v[138:139]
	v_lshl_add_u64 v[4:5], s[92:93], 0, v[142:143]
	v_lshl_add_u64 v[2:3], s[18:19], 0, v[138:139]
	v_lshl_add_u64 v[0:1], s[18:19], 0, v[142:143]
	v_lshl_add_u64 v[6:7], s[94:95], 0, v[136:137]
	s_cselect_b64 s[18:19], -1, 0
	s_cmp_lg_u32 s17, 1
	v_lshl_add_u64 v[10:11], s[94:95], 0, v[140:141]
	s_cbranch_scc1 .LBB0_456
	s_barrier

; #define PG8_WAIT_V(n) asm volatile("s_waitcnt vmcnt(" #n ")" ::: "memory")
; #define PG8_BAR __builtin_amdgcn_s_barrier()
; __device__ __forceinline__ unsigned xb_ld(unsigned* p)              { return __hip_atomic_load(p, __ATOMIC_RELAXED, __HIP_MEMORY_SCOPE_AGENT); }
; __device__ __forceinline__ unsigned xb_add(unsigned* p, unsigned v) { return __hip_atomic_fetch_add(p, v, __ATOMIC_RELAXED, __HIP_MEMORY_SCOPE_AGENT); }
; #define XB_SPIN(cond, bar) do { unsigned _sp = 0; while (cond) { __builtin_amdgcn_s_sleep(1); \
;     if ((++_sp & 255u) == 0u) { if (xb_ld(&(bar)[XB_TMO])) break; if (_sp > XB_SPIN_CAP) { atomicAdd(&(bar)[XB_TMO], 1u); break; } } } } while (0)
; template <class Epi, class Sched, bool ALIGN_EPI = false, bool SP2 = false>
; __device__ __forceinline__ void gemm_phase(PG8_LAS unsigned char* lds, const Gemm g, const Sched& S, const Epi& E, const int tid) {
;     ...
;     PG8_WAIT_V(0);
;     if constexpr (!ALIGN_EPI) { if (wr == 0) PG8_BAR; }
;     PG8_BAR;
; __device__ __forceinline__ void group_barrier(unsigned* ctl, int x, unsigned target, bool coloc) {
;     asm volatile("s_waitcnt vmcnt(0)" ::: "memory");
;     __syncthreads();
;     if (threadIdx.x == 0) {
;         if (!coloc) { __builtin_amdgcn_fence(__ATOMIC_RELEASE, "agent"); asm volatile("s_waitcnt vmcnt(0)" ::: "memory"); }
;         (void)xb_add(&ctl[GB_CNT(x)], 1u);
;         XB_SPIN(xb_ld(&ctl[GB_CNT(x)]) < target, ctl);
.LBB0_492:
	s_waitcnt vmcnt(0)
	v_readlane_b32 s80, v254, 56
	v_readlane_b32 s38, v254, 59
	v_readlane_b32 s81, v254, 57
	v_readlane_b32 s39, v254, 60
	v_readlane_b32 s56, v254, 55
	s_barrier
	s_cmp_lt_u32 s38, 2
	s_cbranch_scc1 .Lap_skip_pl
	s_mov_b32 s99, 1
	v_cmp_eq_u32_e32 vcc, 0, v135
	s_and_saveexec_b64 s[100:101], vcc
	s_cbranch_execz .Lap_done_pl
	s_cmp_eq_u32 s98, 1
	s_cbranch_scc1 .Lap_nowb_pl
	buffer_wbl2 sc1
	s_waitcnt vmcnt(0)

; __device__ __forceinline__ unsigned xb_ld(unsigned* p)              { return __hip_atomic_load(p, __ATOMIC_RELAXED, __HIP_MEMORY_SCOPE_AGENT); }
; #define XB_SPIN(cond, bar) do { unsigned _sp = 0; while (cond) { __builtin_amdgcn_s_sleep(1); \
;     if ((++_sp & 255u) == 0u) { if (xb_ld(&(bar)[XB_TMO])) break; if (_sp > XB_SPIN_CAP) { atomicAdd(&(bar)[XB_TMO], 1u); break; } } } } while (0)
; __device__ __forceinline__ void group_barrier(unsigned* ctl, int x, unsigned target, bool coloc) {
;     ...
;         XB_SPIN(xb_ld(&ctl[GB_CNT(x)]) < target, ctl);
; __global__ void __launch_bounds__(NWAVES * 64, 2) hybrid_fwd(Args args) {
;     ...
;                 if (k == 0) { for (int j = bx; j < (MS / 64) * (INW / 64); j += G) small_gemm_tile<4, 0, DM>(lds, A, Bt, (bf16*)(ws + WS_H + SGRP_BASE + (size_t)(j & 7) * SGRP_BYTES) - (size_t)(MP + (j & 7) * 64) * ZP, ZP, 2 * DM, DM + WPAD, (const float*)(ws + WS_RS), MP + (j & 7) * 64, SMALL_TN(j, INW / 64) * 64, tid); }
;                 else { for (int j = bx; j < (MS / 64) * (DM / 32); j += G) { if (k == 2) small_gemm_tile<2, 0, DM>(lds, (const bf16*)(ws + WS_H + SGRP_BASE + (size_t)(j & 7) * SGRP_BYTES + SGRP_CAT_OFF) - (size_t)(MP + (j & 7) * 64) * DP, Bt, O, OP, DP, DM + WPAD, nullptr, MP + (j & 7) * 64, SMALL_TN(j, DM / 32) * 32, tid); else small_gemm_tile<2, 0, FF>(lds, A, Bt, O, OP, FP, FF + WPAD, nullptr, MP + (j & 7) * 64, SMALL_TN(j, DM / 32) * 32, tid); } }
.Lap_skip_pl:
.LBB0_493:
	v_readfirstlane_b32 vcc_hi, v255
	s_cmp_ge_u32 vcc_hi, 32
	s_cbranch_scc1 .Lws_done_pl
	s_mov_b32 vcc_lo, s55
	s_cmp_eq_u32 vcc_lo, 0
	s_cbranch_scc1 .Lws_done_pl
	v_readlane_b32 s100, v253, 54
	v_readlane_b32 s101, v253, 55
	s_lshl_b32 vcc_lo, vcc_lo, 2
	s_add_u32 vcc_lo, vcc_lo, 0x2000
	s_add_u32 s100, s100, vcc_lo
	s_addc_u32 s101, s101, 0
	s_mov_b32 m0, 0

; __device__ __forceinline__ unsigned xb_ld(unsigned* p)              { return __hip_atomic_load(p, __ATOMIC_RELAXED, __HIP_MEMORY_SCOPE_AGENT); }
; __device__ __forceinline__ unsigned xb_add(unsigned* p, unsigned v) { return __hip_atomic_fetch_add(p, v, __ATOMIC_RELAXED, __HIP_MEMORY_SCOPE_AGENT); }
; #define XB_SPIN(cond, bar) do { unsigned _sp = 0; while (cond) { __builtin_amdgcn_s_sleep(1); \
;     if ((++_sp & 255u) == 0u) { if (xb_ld(&(bar)[XB_TMO])) break; if (_sp > XB_SPIN_CAP) { atomicAdd(&(bar)[XB_TMO], 1u); break; } } } } while (0)
; __device__ __forceinline__ void group_barrier(unsigned* ctl, int x, unsigned target, bool coloc) {
;     ...
;     if (threadIdx.x == 0) {
;         if (!coloc) { __builtin_amdgcn_fence(__ATOMIC_RELEASE, "agent"); asm volatile("s_waitcnt vmcnt(0)" ::: "memory"); }
;         (void)xb_add(&ctl[GB_CNT(x)], 1u);
;         XB_SPIN(xb_ld(&ctl[GB_CNT(x)]) < target, ctl);
.LBB0_705:
	s_mov_b64 s[6:7], exec
	v_mbcnt_lo_u32_b32 v0, s6, 0
	v_mbcnt_hi_u32_b32 v0, s7, v0
	v_cmp_eq_u32_e32 vcc, 0, v0
	s_and_saveexec_b64 s[4:5], vcc
	s_cbranch_execz .LBB0_707
	s_bcnt1_i32_b64 s3, s[6:7]
	v_readlane_b32 s6, v253, 54
	v_mov_b32_e32 v0, s3
	v_readlane_b32 s7, v253, 55
	s_nop 4
	s_cmp_eq_u32 s99, 1
	s_cbranch_scc1 .Lgb_noP
	global_atomic_add v129, v0, s[6:7]
.Lgb_noP:
	s_lshl_b32 s3, s10, 2
	s_add_u32 s3, s3, 0x2000
	s_add_u32 s6, s6, s3
	s_addc_u32 s7, s7, 0
	global_atomic_add v129, v0, s[6:7]

; #define LAS __attribute__((address_space(3)))
; __global__ void __launch_bounds__(NWAVES * 64, 2) hybrid_fwd(Args args) {
;     extern __shared__ __attribute__((aligned(16))) unsigned char lds_raw[];
;     LAS unsigned char* lds = (LAS unsigned char*)lds_raw;
	.amdhsa_kernel _Z10hybrid_fwd4Args
		.amdhsa_group_segment_fixed_size 0
		.amdhsa_private_segment_fixed_size 0
		.amdhsa_kernarg_size 472
		.amdhsa_user_sgpr_count 2
		.amdhsa_user_sgpr_dispatch_ptr 0
		.amdhsa_user_sgpr_queue_ptr 0
		.amdhsa_user_sgpr_kernarg_segment_ptr 1
		.amdhsa_user_sgpr_dispatch_id 0
		.amdhsa_user_sgpr_kernarg_preload_length 0
		.amdhsa_user_sgpr_kernarg_preload_offset 0
		.amdhsa_user_sgpr_private_segment_size 0
		.amdhsa_uses_dynamic_stack 0
		.amdhsa_enable_private_segment 0
		.amdhsa_system_sgpr_workgroup_id_x 1
		.amdhsa_system_sgpr_workgroup_id_y 0
		.amdhsa_system_sgpr_workgroup_id_z 0
		.amdhsa_system_sgpr_workgroup_info 0
		.amdhsa_system_vgpr_workitem_id 2
		.amdhsa_next_free_vgpr 256
		.amdhsa_next_free_sgpr 102
		.amdhsa_accum_offset 256
		.amdhsa_reserve_vcc 1
		.amdhsa_float_round_mode_32 0
		.amdhsa_float_round_mode_16_64 0
		.amdhsa_float_denorm_mode_32 3
		.amdhsa_float_denorm_mode_16_64 3
		.amdhsa_dx10_clamp 1
		.amdhsa_ieee_mode 1
		.amdhsa_fp16_overflow 0
		.amdhsa_tg_split 0
		.amdhsa_exception_fp_ieee_invalid_op 0
		.amdhsa_exception_fp_denorm_src 0
		.amdhsa_exception_fp_ieee_div_zero 0
		.amdhsa_exception_fp_ieee_overflow 0
		.amdhsa_exception_fp_ieee_underflow 0
		.amdhsa_exception_fp_ieee_inexact 0
		.amdhsa_exception_int_div_zero 0
	.end_amdhsa_kernel

; #define LAS __attribute__((address_space(3)))
; __global__ void __launch_bounds__(NWAVES * 64, 2) hybrid_fwd(Args args) {
;     extern __shared__ __attribute__((aligned(16))) unsigned char lds_raw[];
;     LAS unsigned char* lds = (LAS unsigned char*)lds_raw;
amdhsa.kernels:
  - .agpr_count:     0
    .args:
      - .offset:         0
        .size:           216
        .value_kind:     by_value
      - .offset:         216
        .size:           4
        .value_kind:     hidden_block_count_x
      - .offset:         220
        .size:           4
        .value_kind:     hidden_block_count_y
      - .offset:         224
        .size:           4
        .value_kind:     hidden_block_count_z
      - .offset:         228
        .size:           2
        .value_kind:     hidden_group_size_x
      - .offset:         230
        .size:           2
        .value_kind:     hidden_group_size_y
      - .offset:         232
        .size:           2
        .value_kind:     hidden_group_size_z
      - .offset:         234
        .size:           2
        .value_kind:     hidden_remainder_x
      - .offset:         236
        .size:           2
        .value_kind:     hidden_remainder_y
      - .offset:         238
        .size:           2
        .value_kind:     hidden_remainder_z
      - .offset:         256
        .size:           8
        .value_kind:     hidden_global_offset_x
      - .offset:         264
        .size:           8
        .value_kind:     hidden_global_offset_y
      - .offset:         272
        .size:           8
        .value_kind:     hidden_global_offset_z
      - .offset:         280
        .size:           2
        .value_kind:     hidden_grid_dims
      - .offset:         304
        .size:           8
        .value_kind:     hidden_multigrid_sync_arg
      - .offset:         336
        .size:           4
        .value_kind:     hidden_dynamic_lds_size
    .group_segment_fixed_size: 0
    .kernarg_segment_align: 8
    .kernarg_segment_size: 472
    .language:       OpenCL C
    .language_version:
      - 2
      - 0
    .max_flat_workgroup_size: 512
    .name:           _Z10hybrid_fwd4Args
    .private_segment_fixed_size: 0
    .sgpr_count:     108
    .sgpr_spill_count: 158
    .symbol:         _Z10hybrid_fwd4Args.kd
    .uniform_work_group_size: 1
    .uses_dynamic_stack: false
    .vgpr_count:     256
    .vgpr_spill_count: 0
    .wavefront_size: 64
